# P0 ln_in_rows: loop unrolled x2 with two alternating prefetch register sets (2 rows in flight per wave) + DPP reductions
# baseline (speedup 1.0000x reference)
; DI int otid() { int t = __builtin_amdgcn_workitem_id_x(); asm volatile("" : "+v"(t)); return t; }
; DI void ln_in_rows(const float* __restrict__ src, const float* __restrict__ g, const float* __restrict__ bta, const float* __restrict__ w_in, u16* __restrict__ dst, float* __restrict__ G, float* Wg) {
;   const int lane = otid() & 63, wave = otid() >> 6;
;   for (int e = otid(); e < 8192; e += 512) Wg[e] = w_in[(size_t)(e >> 3) * 3592 + 3584 + (e & 7)];
;   __syncthreads();
;   float4 nv[4];
;   { const int row = blockIdx.x * 8 + wave; for (int i = 0; i < 4; ++i) nv[i] = *(const float4*)(src + (size_t)row * 1024 + i * 256 + lane * 4); }
;   for (int row = blockIdx.x * 8 + wave; row < T_TOK; row += gridDim.x * 8) {
;     float4 v[4];
;     float s = 0.f;
;     for (int i = 0; i < 4; ++i) { v[i] = nv[i]; s += v[i].x + v[i].y + v[i].z + v[i].w; }
;     { const int nrow = row + gridDim.x * 8; if (nrow < T_TOK) for (int i = 0; i < 4; ++i) nv[i] = *(const float4*)(src + (size_t)nrow * 1024 + i * 256 + lane * 4); }
.LBB0_165:
	s_or_b64 exec, exec, s[0:1]
	s_add_u32 s0, s68, 0x6300000
	s_addc_u32 s1, s69, 0
	v_writelane_b32 v250, s0, 19
	v_ashrrev_i32_e32 v1, 6, v1
	s_mov_b32 s2, 0x10000
	v_writelane_b32 v250, s1, 20
	s_lshl_b32 s1, s94, 3
	s_lshl_b32 s0, s70, 3
	s_add_u32 s24, s68, 0x6800000
	v_add_u32_e32 v194, s1, v1
	v_writelane_b32 v250, s0, 23
	s_addc_u32 s25, s69, 0
	v_cmp_gt_i32_e32 vcc, s2, v194
	s_waitcnt lgkmcnt(0)
	s_barrier
	v_writelane_b32 v250, s1, 27
	s_and_saveexec_b64 s[4:5], vcc
	s_cbranch_execz .LBB0_172
	v_ashrrev_i32_e32 v195, 31, v194
	v_and_b32_e32 v162, 63, v90
	v_lshlrev_b64 v[2:3], 12, v[194:195]
	v_mbcnt_hi_u32_b32 v34, -1, v203
	v_lshl_add_u64 v[2:3], s[52:53], 0, v[2:3]
	v_lshlrev_b32_e32 v196, 4, v162
	v_mov_b32_e32 v197, 0
	v_and_b32_e32 v1, 64, v34
	v_lshl_add_u64 v[2:3], v[2:3], 0, v[196:197]
	v_add_u32_e32 v35, 64, v1
	v_xor_b32_e32 v1, 32, v34
	global_load_dwordx4 v[178:181], v[2:3], off offset:3072
	global_load_dwordx4 v[182:185], v[2:3], off offset:2048
	global_load_dwordx4 v[186:189], v[2:3], off offset:1024
	global_load_dwordx4 v[190:193], v[2:3], off
	v_cmp_lt_i32_e32 vcc, v1, v35
	v_xor_b32_e32 v2, 16, v34
	v_xor_b32_e32 v36, 2, v34
	v_cndmask_b32_e32 v1, v34, v1, vcc
	v_cmp_lt_i32_e32 vcc, v2, v35
	v_readlane_b32 s0, v250, 19
	v_readlane_b32 s1, v250, 20
	v_cndmask_b32_e32 v2, v34, v2, vcc
	v_lshlrev_b32_e32 v205, 2, v2
	v_xor_b32_e32 v2, 8, v34
	v_cmp_lt_i32_e32 vcc, v2, v35
	v_and_b32_e32 v91, 32, v90
	v_lshrrev_b32_e32 v204, 3, v91
	v_cndmask_b32_e32 v2, v34, v2, vcc
	v_lshlrev_b32_e32 v207, 2, v2
	v_xor_b32_e32 v2, 4, v34
	v_cmp_lt_i32_e32 vcc, v2, v35
	v_lshl_add_u32 v158, v162, 7, 0
	v_lshl_add_u64 v[198:199], s[52:53], 0, v[196:197]
	v_cndmask_b32_e32 v2, v34, v2, vcc
	v_lshlrev_b32_e32 v209, 2, v2
	global_load_dwordx4 v[2:5], v196, s[56:57]
	global_load_dwordx4 v[6:9], v196, s[58:59]
	global_load_dwordx4 v[10:13], v196, s[56:57] offset:1024
	global_load_dwordx4 v[14:17], v196, s[58:59] offset:1024
	global_load_dwordx4 v[18:21], v196, s[56:57] offset:2048
	global_load_dwordx4 v[22:25], v196, s[58:59] offset:2048
	global_load_dwordx4 v[26:29], v196, s[56:57] offset:3072
	global_load_dwordx4 v[30:33], v196, s[58:59] offset:3072
	v_cmp_lt_i32_e32 vcc, v36, v35
	v_bfe_u32 v228, v90, 3, 1
	v_lshlrev_b32_e32 v162, 3, v162
	v_cndmask_b32_e32 v36, v34, v36, vcc
	v_lshlrev_b32_e32 v211, 2, v36
	v_xor_b32_e32 v36, 1, v34
	v_cmp_lt_i32_e32 vcc, v36, v35
	v_mov_b32_e32 v35, v197
	v_mov_b32_e32 v163, v197
	v_cndmask_b32_e32 v34, v34, v36, vcc
	v_lshlrev_b32_e32 v213, 2, v34
	v_and_b32_e32 v34, 7, v90
	v_cmp_eq_u32_e32 vcc, 0, v34
	v_bfe_u32 v34, v90, 1, 5
	v_lshl_add_u64 v[200:201], s[0:1], 0, v[34:35]
	v_cmp_eq_u32_e64 s[0:1], 0, v91
	v_and_b32_e32 v91, 16, v90
	v_lshrrev_b32_e32 v220, 3, v91
	v_cndmask_b32_e64 v202, 0, 4, s[0:1]
	v_cndmask_b32_e64 v206, 1, 5, s[0:1]
	v_cndmask_b32_e64 v208, 5, 1, s[0:1]
	v_cndmask_b32_e64 v210, 2, 6, s[0:1]
	v_cndmask_b32_e64 v212, 6, 2, s[0:1]
	v_cndmask_b32_e64 v214, 3, 7, s[0:1]
	v_cndmask_b32_e64 v216, 7, 3, s[0:1]
	v_cmp_eq_u32_e64 s[0:1], 0, v91
	v_lshrrev_b32_e32 v91, 3, v90
	ds_read_b128 v[34:37], v158
	ds_read_b128 v[38:41], v158 offset:16
	ds_read_b128 v[42:45], v158 offset:32
	ds_read_b128 v[46:49], v158 offset:48
	ds_read_b128 v[50:53], v158 offset:64
	ds_read_b128 v[54:57], v158 offset:80
	ds_read_b128 v[58:61], v158 offset:96
	ds_read_b128 v[62:65], v158 offset:112
	ds_read_b128 v[66:69], v158 offset:8192
	ds_read_b128 v[70:73], v158 offset:8208
	ds_read_b128 v[74:77], v158 offset:8224
	ds_read_b128 v[78:81], v158 offset:8240
	ds_read_b128 v[82:85], v158 offset:8256
	ds_read_b128 v[86:89], v158 offset:8272
	v_bitop3_b32 v196, v91, 1, v91 bitop3:0xc
	ds_read_b128 v[90:93], v158 offset:8288
	ds_read_b128 v[94:97], v158 offset:8304
	ds_read_b128 v[98:101], v158 offset:16384
	ds_read_b128 v[102:105], v158 offset:16400
	ds_read_b128 v[106:109], v158 offset:16416
	ds_read_b128 v[110:113], v158 offset:16432
	ds_read_b128 v[114:117], v158 offset:16448
	ds_read_b128 v[118:121], v158 offset:16464
	ds_read_b128 v[122:125], v158 offset:16480
	ds_read_b128 v[126:129], v158 offset:16496
	ds_read_b128 v[130:133], v158 offset:24576
	ds_read_b128 v[134:137], v158 offset:24592
	ds_read_b128 v[138:141], v158 offset:24608
	ds_read_b128 v[142:145], v158 offset:24624
	ds_read_b128 v[146:149], v158 offset:24640
	ds_read_b128 v[150:153], v158 offset:24656
	ds_read_b128 v[154:157], v158 offset:24672
	ds_read_b128 v[158:161], v158 offset:24688
	v_lshlrev_b32_e32 v1, 2, v1
	v_cndmask_b32_e64 v218, 0, 2, s[0:1]
	v_cndmask_b32_e64 v224, 1, 3, s[0:1]
	v_cndmask_b32_e64 v226, 3, 1, s[0:1]
	v_mov_b32_e32 v229, v197
	v_lshl_add_u64 v[230:231], s[24:25], 0, v[162:163]
	s_mov_b64 s[6:7], 0
	s_mov_b32 s3, 0xffff
	v_mov_b32_e32 v215, 0x3727c5ac
	s_mov_b32 s12, 0x800000
	s_waitcnt vmcnt(11)
	v_mov_b64_e32 v[174:175], v[178:179]
	s_waitcnt vmcnt(10)
	v_mov_b64_e32 v[170:171], v[182:183]
	s_waitcnt vmcnt(9)
	v_mov_b64_e32 v[166:167], v[186:187]
	s_waitcnt vmcnt(8)
	v_mov_b64_e32 v[162:163], v[190:191]
	v_mov_b64_e32 v[164:165], v[192:193]
	v_mov_b64_e32 v[168:169], v[188:189]
	v_mov_b64_e32 v[172:173], v[184:185]
	v_mov_b64_e32 v[176:177], v[180:181]
	v_readlane_b32 s0, v250, 23
	s_nop 1
	v_add_u32_e32 v196, s0, v194
	v_min_i32_e32 v196, s3, v196
	v_ashrrev_i32_e32 v197, 31, v196
	v_lshlrev_b64 v[196:197], 12, v[196:197]
	v_lshl_add_u64 v[248:249], v[198:199], 0, v[196:197]
	global_load_dwordx4 v[162:165], v[248:249], off
	global_load_dwordx4 v[166:169], v[248:249], off offset:1024
	global_load_dwordx4 v[170:173], v[248:249], off offset:2048
	global_load_dwordx4 v[174:177], v[248:249], off offset:3072
	s_waitcnt vmcnt(0)
	s_branch .LBB0_168
; DI float wsum(float v) { for (int o = 32; o; o >>= 1) v += __shfl_xor(v, o); return v; }
; DI void ln_in_rows(const float* __restrict__ src, const float* __restrict__ g, const float* __restrict__ bta, const float* __restrict__ w_in, u16* __restrict__ dst, float* __restrict__ G, float* Wg) {
;     ...
;   for (int row = blockIdx.x * 8 + wave; row < T_TOK; row += gridDim.x * 8) {
;     float4 v[4];
;     float s = 0.f;
;     for (int i = 0; i < 4; ++i) { v[i] = nv[i]; s += v[i].x + v[i].y + v[i].z + v[i].w; }
;     { const int nrow = row + gridDim.x * 8; if (nrow < T_TOK) for (int i = 0; i < 4; ++i) nv[i] = *(const float4*)(src + (size_t)nrow * 1024 + i * 256 + lane * 4); }
;     const float mu = wsum(s) * (1.f / 1024.f);
;     float q = 0.f;
;     for (int i = 0; i < 4; ++i) { float a = v[i].x - mu, b = v[i].y - mu, c = v[i].z - mu, d = v[i].w - mu; q += a * a + b * b + c * c + d * d; }
;     const float rstd = rsqrtf(wsum(q) * (1.f / 1024.f) + LN_EPS);
.LBB0_168:
	v_readlane_b32 s0, v250, 23
	s_nop 1
	v_add_u32_e32 v232, s0, v194
	v_add_u32_e32 v196, s0, v232
	v_min_i32_e32 v196, s3, v196
	v_cmp_lt_i32_e64 s[0:1], s3, v232
	v_ashrrev_i32_e32 v197, 31, v196
	v_lshlrev_b64 v[196:197], 12, v[196:197]
	v_lshl_add_u64 v[248:249], v[198:199], 0, v[196:197]
	global_load_dwordx4 v[204:207], v[248:249], off
	global_load_dwordx4 v[208:211], v[248:249], off offset:1024
	global_load_dwordx4 v[224:227], v[248:249], off offset:2048
	global_load_dwordx4 v[244:247], v[248:249], off offset:3072
	v_add_f32_e32 v195, v190, v191
	v_add_f32_e32 v195, v195, v192
	v_add_f32_e32 v217, v186, v187
	v_add_f32_e32 v195, v195, v193
	v_add_f32_e32 v217, v217, v188
	v_add_f32_e32 v195, 0, v195
	v_add_f32_e32 v217, v217, v189
	v_add_f32_e32 v195, v195, v217
	v_add_f32_e32 v217, v182, v183
	v_add_f32_e32 v217, v217, v184
	v_add_f32_e32 v217, v217, v185
	v_add_f32_e32 v195, v195, v217
	v_add_f32_e32 v217, v178, v179
	v_add_f32_e32 v217, v217, v180
	v_add_f32_e32 v217, v217, v181
	v_add_f32_e32 v195, v195, v217
	s_nop 1
	v_add_f32_dpp v195, v195, v195 row_shr:1 row_mask:0xf bank_mask:0xf
	s_nop 1
	v_add_f32_dpp v195, v195, v195 row_shr:2 row_mask:0xf bank_mask:0xf
	s_nop 1
	v_add_f32_dpp v195, v195, v195 row_shr:4 row_mask:0xf bank_mask:0xf
	s_nop 1
	v_add_f32_dpp v195, v195, v195 row_shr:8 row_mask:0xf bank_mask:0xf
	s_nop 1
	v_add_f32_dpp v195, v195, v195 row_bcast:15 row_mask:0xa bank_mask:0xf
	s_nop 1
	v_add_f32_dpp v195, v195, v195 row_bcast:31 row_mask:0xc bank_mask:0xf
	s_nop 0
	v_readlane_b32 s72, v195, 63
	s_nop 1
	v_mov_b32_e32 v195, s72
	v_mul_f32_e32 v234, 0x3a800000, v195
	v_pk_add_f32 v[190:191], v[190:191], v[234:235] op_sel_hi:[1,0] neg_lo:[0,1] neg_hi:[0,1]
	v_pk_add_f32 v[186:187], v[186:187], v[234:235] op_sel_hi:[1,0] neg_lo:[0,1] neg_hi:[0,1]
	v_mov_b32_e32 v240, v191
	v_mov_b32_e32 v241, v187
	v_pk_add_f32 v[192:193], v[192:193], v[234:235] op_sel_hi:[1,0] neg_lo:[0,1] neg_hi:[0,1]
	v_pk_add_f32 v[188:189], v[188:189], v[234:235] op_sel_hi:[1,0] neg_lo:[0,1] neg_hi:[0,1]
	v_pk_add_f32 v[182:183], v[182:183], v[234:235] op_sel_hi:[1,0] neg_lo:[0,1] neg_hi:[0,1]
	v_pk_add_f32 v[236:237], v[180:181], v[234:235] op_sel_hi:[1,0] neg_lo:[0,1] neg_hi:[0,1]
	v_pk_add_f32 v[180:181], v[178:179], v[234:235] op_sel_hi:[1,0] neg_lo:[0,1] neg_hi:[0,1]
	v_mov_b32_e32 v238, v190
	v_mov_b32_e32 v239, v186
	v_pk_mul_f32 v[240:241], v[240:241], v[240:241]
	v_mov_b32_e32 v178, v192
	v_mov_b32_e32 v179, v188
	v_pk_fma_f32 v[238:239], v[238:239], v[238:239], v[240:241]
	v_mov_b32_e32 v240, v181
	v_mov_b32_e32 v241, v183
	v_pk_add_f32 v[184:185], v[184:185], v[234:235] op_sel_hi:[1,0] neg_lo:[0,1] neg_hi:[0,1]
	v_pk_fma_f32 v[178:179], v[178:179], v[178:179], v[238:239]
	v_mov_b32_e32 v238, v180
	v_mov_b32_e32 v239, v182
	v_pk_mul_f32 v[240:241], v[240:241], v[240:241]
	v_mov_b32_e32 v234, v193
	v_mov_b32_e32 v235, v189
	v_mov_b32_e32 v242, v236
	v_mov_b32_e32 v243, v184
	v_pk_fma_f32 v[238:239], v[238:239], v[238:239], v[240:241]
	v_pk_fma_f32 v[178:179], v[234:235], v[234:235], v[178:179]
	v_mov_b32_e32 v234, v237
	v_mov_b32_e32 v235, v185
	v_pk_fma_f32 v[238:239], v[242:243], v[242:243], v[238:239]
	v_add_f32_e32 v178, v178, v179
	v_pk_fma_f32 v[234:235], v[234:235], v[234:235], v[238:239]
	v_ashrrev_i32_e32 v195, 31, v194
	v_add_f32_e32 v178, v235, v178
	v_add_f32_e32 v178, v234, v178
	s_nop 1
	v_add_f32_dpp v178, v178, v178 row_shr:1 row_mask:0xf bank_mask:0xf
	s_nop 1
	v_add_f32_dpp v178, v178, v178 row_shr:2 row_mask:0xf bank_mask:0xf
	s_nop 1
	v_add_f32_dpp v178, v178, v178 row_shr:4 row_mask:0xf bank_mask:0xf
	s_nop 1
	v_add_f32_dpp v178, v178, v178 row_shr:8 row_mask:0xf bank_mask:0xf
	s_nop 1
	v_add_f32_dpp v178, v178, v178 row_bcast:15 row_mask:0xa bank_mask:0xf
	s_nop 1
	v_add_f32_dpp v178, v178, v178 row_bcast:31 row_mask:0xc bank_mask:0xf
	s_nop 0
	v_readlane_b32 s73, v178, 63
	s_nop 1
	v_mov_b32_e32 v178, s73
	v_fmamk_f32 v178, v178, 0x3a800000, v215
	v_mul_f32_e32 v179, 0x4b800000, v178
	v_cmp_gt_f32_e64 s[8:9], s12, v178
	s_nop 1
	v_cndmask_b32_e64 v178, v178, v179, s[8:9]
	v_rsq_f32_e32 v217, v178
	v_lshlrev_b64 v[178:179], 11, v[194:195]
	v_lshl_add_u64 v[178:179], v[230:231], 0, v[178:179]
	v_mul_f32_e32 v219, 0x45800000, v217
	v_cndmask_b32_e64 v238, v217, v219, s[8:9]
	v_pk_mul_f32 v[190:191], v[190:191], v[238:239] op_sel_hi:[1,0]
	v_pk_mul_f32 v[234:235], v[192:193], v[238:239] op_sel_hi:[1,0]
	v_pk_mul_f32 v[182:183], v[182:183], v[238:239] op_sel_hi:[1,0]
	v_pk_fma_f32 v[192:193], v[2:3], v[190:191], v[6:7]
	v_pk_mul_f32 v[240:241], v[184:185], v[238:239] op_sel_hi:[1,0]
	v_pk_fma_f32 v[184:185], v[18:19], v[182:183], v[22:23]
	v_pk_mul_f32 v[182:183], v[236:237], v[238:239] op_sel_hi:[1,0]
	v_pk_fma_f32 v[236:237], v[34:35], v[192:193], 0 op_sel_hi:[1,0,0]
	v_pk_mul_f32 v[186:187], v[186:187], v[238:239] op_sel_hi:[1,0]
	v_pk_mul_f32 v[188:189], v[188:189], v[238:239] op_sel_hi:[1,0]
	v_pk_mul_f32 v[180:181], v[180:181], v[238:239] op_sel_hi:[1,0]
	v_pk_fma_f32 v[234:235], v[4:5], v[234:235], v[8:9]
	v_pk_fma_f32 v[236:237], v[42:43], v[192:193], v[236:237] op_sel:[0,1,0]
	v_pk_fma_f32 v[238:239], v[36:37], v[192:193], 0 op_sel_hi:[1,0,0]
	v_pk_fma_f32 v[236:237], v[50:51], v[234:235], v[236:237] op_sel_hi:[1,0,1]
	v_pk_fma_f32 v[238:239], v[44:45], v[192:193], v[238:239] op_sel:[0,1,0]
	v_pk_fma_f32 v[190:191], v[10:11], v[186:187], v[14:15]
	v_pk_fma_f32 v[186:187], v[20:21], v[240:241], v[24:25]
	v_pk_fma_f32 v[236:237], v[58:59], v[234:235], v[236:237] op_sel:[0,1,0]
	v_pk_fma_f32 v[238:239], v[52:53], v[234:235], v[238:239] op_sel_hi:[1,0,1]
	v_pk_fma_f32 v[240:241], v[38:39], v[192:193], 0 op_sel_hi:[1,0,0]
; DI unsigned pack2(float a, float b) { const f32x2 v = {a, b}; return __builtin_bit_cast(unsigned, __builtin_convertvector(v, bf16v2)); }
; DI void ln_in_rows(const float* __restrict__ src, const float* __restrict__ g, const float* __restrict__ bta, const float* __restrict__ w_in, u16* __restrict__ dst, float* __restrict__ G, float* Wg) {
;     ...
;     for (int i = 0; i < 4; ++i) {
;       const int c0 = i * 256 + lane * 4;
;       float4 gg = *(const float4*)(g + c0), bb = *(const float4*)(bta + c0);
;       float y[4];
;       y[0] = (v[i].x - mu) * rstd * gg.x + bb.x; y[1] = (v[i].y - mu) * rstd * gg.y + bb.y; y[2] = (v[i].z - mu) * rstd * gg.z + bb.z; y[3] = (v[i].w - mu) * rstd * gg.w + bb.w;
;       uint2 o; o.x = pack2(y[0], y[1]); o.y = pack2(y[2], y[3]);
;       *(uint2*)(dst + (size_t)row * 1024 + c0) = o;
; #pragma unroll
;       for (int e = 0; e < 4; ++e) {
;         const float4 w0 = *(const float4*)(Wg + (c0 + e) * 8), w1 = *(const float4*)(Wg + (c0 + e) * 8 + 4);
;         pg[0] += y[e] * w0.x; pg[1] += y[e] * w0.y; pg[2] += y[e] * w0.z; pg[3] += y[e] * w0.w;
;         pg[4] += y[e] * w1.x; pg[5] += y[e] * w1.y; pg[6] += y[e] * w1.z; pg[7] += y[e] * w1.w;
;       }
;     }
; #pragma unroll
;     for (int off = 32; off >= 8; off >>= 1) {
;       const bool up = (lane & off) != 0;
;       const int nkeep = off >> 3;
; #pragma unroll
;       for (int i = 0; i < 4; ++i) if (i < nkeep) {
;         const float send = up ? pg[i] : pg[i + nkeep];
;         const float keep = up ? pg[i + nkeep] : pg[i];
;         pg[i] = keep + __shfl_xor(send, off);
;       }
;     }
;     float tot = pg[0];
;     tot += __shfl_xor(tot, 4); tot += __shfl_xor(tot, 2); tot += __shfl_xor(tot, 1);
	v_pk_fma_f32 v[236:237], v[66:67], v[190:191], v[236:237] op_sel_hi:[1,0,1]
	v_pk_fma_f32 v[238:239], v[60:61], v[234:235], v[238:239] op_sel:[0,1,0]
	v_pk_fma_f32 v[240:241], v[46:47], v[192:193], v[240:241] op_sel:[0,1,0]
	v_pk_fma_f32 v[188:189], v[12:13], v[188:189], v[16:17]
	v_pk_fma_f32 v[236:237], v[74:75], v[190:191], v[236:237] op_sel:[0,1,0]
	v_pk_fma_f32 v[238:239], v[68:69], v[190:191], v[238:239] op_sel_hi:[1,0,1]
	v_pk_fma_f32 v[240:241], v[54:55], v[234:235], v[240:241] op_sel_hi:[1,0,1]
	v_pk_fma_f32 v[242:243], v[40:41], v[192:193], 0 op_sel_hi:[1,0,0]
	v_pk_fma_f32 v[236:237], v[82:83], v[188:189], v[236:237] op_sel_hi:[1,0,1]
	v_pk_fma_f32 v[238:239], v[76:77], v[190:191], v[238:239] op_sel:[0,1,0]
	v_pk_fma_f32 v[240:241], v[62:63], v[234:235], v[240:241] op_sel:[0,1,0]
	v_pk_fma_f32 v[242:243], v[48:49], v[192:193], v[242:243] op_sel:[0,1,0]
	v_pk_fma_f32 v[236:237], v[90:91], v[188:189], v[236:237] op_sel:[0,1,0]
	v_pk_fma_f32 v[238:239], v[84:85], v[188:189], v[238:239] op_sel_hi:[1,0,1]
	v_pk_fma_f32 v[240:241], v[70:71], v[190:191], v[240:241] op_sel_hi:[1,0,1]
	v_pk_fma_f32 v[242:243], v[56:57], v[234:235], v[242:243] op_sel_hi:[1,0,1]
	v_pk_fma_f32 v[236:237], v[98:99], v[184:185], v[236:237] op_sel_hi:[1,0,1]
	v_pk_fma_f32 v[238:239], v[92:93], v[188:189], v[238:239] op_sel:[0,1,0]
	v_pk_fma_f32 v[240:241], v[78:79], v[190:191], v[240:241] op_sel:[0,1,0]
	v_pk_fma_f32 v[242:243], v[64:65], v[234:235], v[242:243] op_sel:[0,1,0]
	v_pk_fma_f32 v[236:237], v[106:107], v[184:185], v[236:237] op_sel:[0,1,0]
	v_pk_fma_f32 v[238:239], v[100:101], v[184:185], v[238:239] op_sel_hi:[1,0,1]
	v_pk_fma_f32 v[240:241], v[86:87], v[188:189], v[240:241] op_sel_hi:[1,0,1]
	v_pk_fma_f32 v[242:243], v[72:73], v[190:191], v[242:243] op_sel_hi:[1,0,1]
	v_pk_fma_f32 v[236:237], v[114:115], v[186:187], v[236:237] op_sel_hi:[1,0,1]
	v_pk_fma_f32 v[238:239], v[108:109], v[184:185], v[238:239] op_sel:[0,1,0]
	v_pk_fma_f32 v[240:241], v[94:95], v[188:189], v[240:241] op_sel:[0,1,0]
	v_pk_fma_f32 v[242:243], v[80:81], v[190:191], v[242:243] op_sel:[0,1,0]
	v_pk_fma_f32 v[180:181], v[26:27], v[180:181], v[30:31]
	v_pk_fma_f32 v[236:237], v[122:123], v[186:187], v[236:237] op_sel:[0,1,0]
	v_pk_fma_f32 v[238:239], v[116:117], v[186:187], v[238:239] op_sel_hi:[1,0,1]
	v_pk_fma_f32 v[240:241], v[102:103], v[184:185], v[240:241] op_sel_hi:[1,0,1]
	v_pk_fma_f32 v[242:243], v[88:89], v[188:189], v[242:243] op_sel_hi:[1,0,1]
	v_pk_fma_f32 v[236:237], v[130:131], v[180:181], v[236:237] op_sel_hi:[1,0,1]
	v_pk_fma_f32 v[238:239], v[124:125], v[186:187], v[238:239] op_sel:[0,1,0]
	v_pk_fma_f32 v[240:241], v[110:111], v[184:185], v[240:241] op_sel:[0,1,0]
	v_pk_fma_f32 v[242:243], v[96:97], v[188:189], v[242:243] op_sel:[0,1,0]
	v_pk_fma_f32 v[182:183], v[28:29], v[182:183], v[32:33]
	v_pk_fma_f32 v[236:237], v[138:139], v[180:181], v[236:237] op_sel:[0,1,0]
	v_pk_fma_f32 v[238:239], v[132:133], v[180:181], v[238:239] op_sel_hi:[1,0,1]
	v_pk_fma_f32 v[240:241], v[118:119], v[186:187], v[240:241] op_sel_hi:[1,0,1]
	v_pk_fma_f32 v[242:243], v[104:105], v[184:185], v[242:243] op_sel_hi:[1,0,1]
	v_pk_fma_f32 v[236:237], v[146:147], v[182:183], v[236:237] op_sel_hi:[1,0,1]
	v_pk_fma_f32 v[238:239], v[140:141], v[180:181], v[238:239] op_sel:[0,1,0]
	v_pk_fma_f32 v[240:241], v[126:127], v[186:187], v[240:241] op_sel:[0,1,0]
	v_pk_fma_f32 v[242:243], v[112:113], v[184:185], v[242:243] op_sel:[0,1,0]
	v_pk_fma_f32 v[236:237], v[154:155], v[182:183], v[236:237] op_sel:[0,1,0]
	v_pk_fma_f32 v[238:239], v[148:149], v[182:183], v[238:239] op_sel_hi:[1,0,1]
	v_pk_fma_f32 v[240:241], v[180:181], v[134:135], v[240:241] op_sel_hi:[0,1,1]
	v_pk_fma_f32 v[242:243], v[120:121], v[186:187], v[242:243] op_sel_hi:[1,0,1]
	v_pk_fma_f32 v[238:239], v[156:157], v[182:183], v[238:239] op_sel:[0,1,0]
	v_pk_fma_f32 v[240:241], v[180:181], v[142:143], v[240:241] op_sel:[1,0,0]
	v_pk_fma_f32 v[242:243], v[128:129], v[186:187], v[242:243] op_sel:[0,1,0]
	v_pk_fma_f32 v[240:241], v[182:183], v[150:151], v[240:241] op_sel_hi:[0,1,1]
	v_pk_fma_f32 v[242:243], v[180:181], v[136:137], v[242:243] op_sel_hi:[0,1,1]
	v_pk_fma_f32 v[240:241], v[182:183], v[158:159], v[240:241] op_sel:[1,0,0]
	v_pk_fma_f32 v[242:243], v[180:181], v[144:145], v[242:243] op_sel:[1,0,0]
	v_pk_fma_f32 v[242:243], v[182:183], v[152:153], v[242:243] op_sel_hi:[0,1,1]
	v_pk_fma_f32 v[242:243], v[182:183], v[160:161], v[242:243] op_sel:[1,0,0]
	v_cvt_pk_bf16_f32 v192, v192, v193
	v_cvt_pk_bf16_f32 v193, v234, v235
	global_store_dwordx2 v[178:179], v[192:193], off
	v_cvt_pk_bf16_f32 v190, v190, v191
	v_cvt_pk_bf16_f32 v191, v188, v189
	v_cvt_pk_bf16_f32 v188, v184, v185
	v_cvt_pk_bf16_f32 v189, v186, v187
	v_cvt_pk_bf16_f32 v180, v180, v181
	v_cvt_pk_bf16_f32 v181, v182, v183
	global_store_dwordx2 v[178:179], v[190:191], off offset:512
	global_store_dwordx2 v[178:179], v[188:189], off offset:1024
	global_store_dwordx2 v[178:179], v[180:181], off offset:1536
	v_add_f32_dpp v236, v236, v236 row_shr:1 row_mask:0xf bank_mask:0xf
	v_add_f32_dpp v237, v237, v237 row_shr:1 row_mask:0xf bank_mask:0xf
	v_add_f32_dpp v238, v238, v238 row_shr:1 row_mask:0xf bank_mask:0xf
	v_add_f32_dpp v239, v239, v239 row_shr:1 row_mask:0xf bank_mask:0xf
	v_add_f32_dpp v240, v240, v240 row_shr:1 row_mask:0xf bank_mask:0xf
	v_add_f32_dpp v241, v241, v241 row_shr:1 row_mask:0xf bank_mask:0xf
	v_add_f32_dpp v242, v242, v242 row_shr:1 row_mask:0xf bank_mask:0xf
	v_add_f32_dpp v243, v243, v243 row_shr:1 row_mask:0xf bank_mask:0xf
	v_add_f32_dpp v236, v236, v236 row_shr:2 row_mask:0xf bank_mask:0xf
	v_add_f32_dpp v237, v237, v237 row_shr:2 row_mask:0xf bank_mask:0xf
; DI float wsum(float v) { for (int o = 32; o; o >>= 1) v += __shfl_xor(v, o); return v; }
; DI void ln_in_rows(const float* __restrict__ src, const float* __restrict__ g, const float* __restrict__ bta, const float* __restrict__ w_in, u16* __restrict__ dst, float* __restrict__ G, float* Wg) {
;     ...
;   for (int row = blockIdx.x * 8 + wave; row < T_TOK; row += gridDim.x * 8) {
;     float4 v[4];
;     float s = 0.f;
;     for (int i = 0; i < 4; ++i) { v[i] = nv[i]; s += v[i].x + v[i].y + v[i].z + v[i].w; }
;     { const int nrow = row + gridDim.x * 8; if (nrow < T_TOK) for (int i = 0; i < 4; ++i) nv[i] = *(const float4*)(src + (size_t)nrow * 1024 + i * 256 + lane * 4); }
;     const float mu = wsum(s) * (1.f / 1024.f);
;     float q = 0.f;
;     for (int i = 0; i < 4; ++i) { float a = v[i].x - mu, b = v[i].y - mu, c = v[i].z - mu, d = v[i].w - mu; q += a * a + b * b + c * c + d * d; }
;     const float rstd = rsqrtf(wsum(q) * (1.f / 1024.f) + LN_EPS);
;     ...
; #pragma unroll
;     for (int off = 32; off >= 8; off >>= 1) {
;       const bool up = (lane & off) != 0;
;       const int nkeep = off >> 3;
; #pragma unroll
;       for (int i = 0; i < 4; ++i) if (i < nkeep) {
;         const float send = up ? pg[i] : pg[i + nkeep];
;         const float keep = up ? pg[i + nkeep] : pg[i];
;         pg[i] = keep + __shfl_xor(send, off);
;       }
;     }
;     float tot = pg[0];
;     tot += __shfl_xor(tot, 4); tot += __shfl_xor(tot, 2); tot += __shfl_xor(tot, 1);
;     if ((lane & 7) == 0) G[(size_t)row * 8 + (lane >> 3)] = tot;
	v_add_f32_dpp v238, v238, v238 row_shr:2 row_mask:0xf bank_mask:0xf
	v_add_f32_dpp v239, v239, v239 row_shr:2 row_mask:0xf bank_mask:0xf
	v_add_f32_dpp v240, v240, v240 row_shr:2 row_mask:0xf bank_mask:0xf
	v_add_f32_dpp v241, v241, v241 row_shr:2 row_mask:0xf bank_mask:0xf
	v_add_f32_dpp v242, v242, v242 row_shr:2 row_mask:0xf bank_mask:0xf
	v_add_f32_dpp v243, v243, v243 row_shr:2 row_mask:0xf bank_mask:0xf
	v_add_f32_dpp v236, v236, v236 row_shr:4 row_mask:0xf bank_mask:0xf
	v_add_f32_dpp v237, v237, v237 row_shr:4 row_mask:0xf bank_mask:0xf
	v_add_f32_dpp v238, v238, v238 row_shr:4 row_mask:0xf bank_mask:0xf
	v_add_f32_dpp v239, v239, v239 row_shr:4 row_mask:0xf bank_mask:0xf
	v_add_f32_dpp v240, v240, v240 row_shr:4 row_mask:0xf bank_mask:0xf
	v_add_f32_dpp v241, v241, v241 row_shr:4 row_mask:0xf bank_mask:0xf
	v_add_f32_dpp v242, v242, v242 row_shr:4 row_mask:0xf bank_mask:0xf
	v_add_f32_dpp v243, v243, v243 row_shr:4 row_mask:0xf bank_mask:0xf
	v_add_f32_dpp v236, v236, v236 row_shr:8 row_mask:0xf bank_mask:0xf
	v_add_f32_dpp v237, v237, v237 row_shr:8 row_mask:0xf bank_mask:0xf
	v_add_f32_dpp v238, v238, v238 row_shr:8 row_mask:0xf bank_mask:0xf
	v_add_f32_dpp v239, v239, v239 row_shr:8 row_mask:0xf bank_mask:0xf
	v_add_f32_dpp v240, v240, v240 row_shr:8 row_mask:0xf bank_mask:0xf
	v_add_f32_dpp v241, v241, v241 row_shr:8 row_mask:0xf bank_mask:0xf
	v_add_f32_dpp v242, v242, v242 row_shr:8 row_mask:0xf bank_mask:0xf
	v_add_f32_dpp v243, v243, v243 row_shr:8 row_mask:0xf bank_mask:0xf
	v_add_f32_dpp v236, v236, v236 row_bcast:15 row_mask:0xa bank_mask:0xf
	v_add_f32_dpp v237, v237, v237 row_bcast:15 row_mask:0xa bank_mask:0xf
	v_add_f32_dpp v238, v238, v238 row_bcast:15 row_mask:0xa bank_mask:0xf
	v_add_f32_dpp v239, v239, v239 row_bcast:15 row_mask:0xa bank_mask:0xf
	v_add_f32_dpp v240, v240, v240 row_bcast:15 row_mask:0xa bank_mask:0xf
	v_add_f32_dpp v241, v241, v241 row_bcast:15 row_mask:0xa bank_mask:0xf
	v_add_f32_dpp v242, v242, v242 row_bcast:15 row_mask:0xa bank_mask:0xf
	v_add_f32_dpp v243, v243, v243 row_bcast:15 row_mask:0xa bank_mask:0xf
	v_add_f32_dpp v236, v236, v236 row_bcast:31 row_mask:0xc bank_mask:0xf
	v_add_f32_dpp v237, v237, v237 row_bcast:31 row_mask:0xc bank_mask:0xf
	v_add_f32_dpp v238, v238, v238 row_bcast:31 row_mask:0xc bank_mask:0xf
	v_add_f32_dpp v239, v239, v239 row_bcast:31 row_mask:0xc bank_mask:0xf
	v_add_f32_dpp v240, v240, v240 row_bcast:31 row_mask:0xc bank_mask:0xf
	v_add_f32_dpp v241, v241, v241 row_bcast:31 row_mask:0xc bank_mask:0xf
	v_add_f32_dpp v242, v242, v242 row_bcast:31 row_mask:0xc bank_mask:0xf
	v_add_f32_dpp v243, v243, v243 row_bcast:31 row_mask:0xc bank_mask:0xf
	v_readlane_b32 s72, v236, 63
	v_readlane_b32 s73, v237, 63
	v_readlane_b32 s74, v238, 63
	v_readlane_b32 s75, v239, 63
	v_readlane_b32 s76, v240, 63
	v_readlane_b32 s77, v241, 63
	v_readlane_b32 s78, v242, 63
	v_readlane_b32 s79, v243, 63
	v_writelane_b32 v217, s72, 0
	v_writelane_b32 v217, s73, 8
	v_writelane_b32 v217, s74, 16
	v_writelane_b32 v217, s75, 24
	v_writelane_b32 v217, s76, 32
	v_writelane_b32 v217, s77, 40
	v_writelane_b32 v217, s78, 48
	v_writelane_b32 v217, s79, 56
	s_and_saveexec_b64 s[8:9], vcc
	s_cbranch_execz .Lln_botE
	v_lshlrev_b64 v[178:179], 5, v[194:195]
	v_lshl_add_u64 v[178:179], v[200:201], 0, v[178:179]
	global_store_dword v[178:179], v217, off
.Lln_botE:
	s_or_b64 exec, exec, s[8:9]
	s_waitcnt vmcnt(14)
	s_and_b64 s[0:1], exec, s[0:1]
	s_or_b64 s[6:7], s[0:1], s[6:7]
	v_mov_b32_e32 v194, v232
	v_mov_b64_e32 v[190:191], v[162:163]
	v_mov_b64_e32 v[192:193], v[164:165]
	v_mov_b64_e32 v[186:187], v[166:167]
	v_mov_b64_e32 v[188:189], v[168:169]
	v_mov_b64_e32 v[182:183], v[170:171]
	v_mov_b64_e32 v[184:185], v[172:173]
	v_mov_b64_e32 v[178:179], v[174:175]
	v_mov_b64_e32 v[180:181], v[176:177]
	s_waitcnt lgkmcnt(0)
	s_andn2_b64 exec, exec, s[6:7]
	s_cbranch_execz .LBB0_172
.Lln_O:
	v_readlane_b32 s0, v250, 23
	s_nop 1
	v_add_u32_e32 v232, s0, v194
	v_add_u32_e32 v196, s0, v232
	v_min_i32_e32 v196, s3, v196
	v_cmp_lt_i32_e64 s[0:1], s3, v232
	v_ashrrev_i32_e32 v197, 31, v196
	v_lshlrev_b64 v[196:197], 12, v[196:197]
	v_lshl_add_u64 v[248:249], v[198:199], 0, v[196:197]
	global_load_dwordx4 v[162:165], v[248:249], off
	global_load_dwordx4 v[166:169], v[248:249], off offset:1024
	global_load_dwordx4 v[170:173], v[248:249], off offset:2048
	global_load_dwordx4 v[174:177], v[248:249], off offset:3072
	v_add_f32_e32 v195, v190, v191
	v_add_f32_e32 v195, v195, v192
	v_add_f32_e32 v217, v186, v187
	v_add_f32_e32 v195, v195, v193
	v_add_f32_e32 v217, v217, v188
	v_add_f32_e32 v195, 0, v195
	v_add_f32_e32 v217, v217, v189
	v_add_f32_e32 v195, v195, v217
	v_add_f32_e32 v217, v182, v183
	v_add_f32_e32 v217, v217, v184
	v_add_f32_e32 v217, v217, v185
	v_add_f32_e32 v195, v195, v217
	v_add_f32_e32 v217, v178, v179
	v_add_f32_e32 v217, v217, v180
	v_add_f32_e32 v217, v217, v181
	v_add_f32_e32 v195, v195, v217
	s_nop 1
	v_add_f32_dpp v195, v195, v195 row_shr:1 row_mask:0xf bank_mask:0xf
	s_nop 1
	v_add_f32_dpp v195, v195, v195 row_shr:2 row_mask:0xf bank_mask:0xf
	s_nop 1
	v_add_f32_dpp v195, v195, v195 row_shr:4 row_mask:0xf bank_mask:0xf
	s_nop 1
	v_add_f32_dpp v195, v195, v195 row_shr:8 row_mask:0xf bank_mask:0xf
	s_nop 1
	v_add_f32_dpp v195, v195, v195 row_bcast:15 row_mask:0xa bank_mask:0xf
	s_nop 1
	v_add_f32_dpp v195, v195, v195 row_bcast:31 row_mask:0xc bank_mask:0xf
	s_nop 0
	v_readlane_b32 s72, v195, 63
	s_nop 1
	v_mov_b32_e32 v195, s72
	v_mul_f32_e32 v234, 0x3a800000, v195
	v_pk_add_f32 v[190:191], v[190:191], v[234:235] op_sel_hi:[1,0] neg_lo:[0,1] neg_hi:[0,1]
; DI unsigned pack2(float a, float b) { const f32x2 v = {a, b}; return __builtin_bit_cast(unsigned, __builtin_convertvector(v, bf16v2)); }
; DI float wsum(float v) { for (int o = 32; o; o >>= 1) v += __shfl_xor(v, o); return v; }
; DI void ln_in_rows(const float* __restrict__ src, const float* __restrict__ g, const float* __restrict__ bta, const float* __restrict__ w_in, u16* __restrict__ dst, float* __restrict__ G, float* Wg) {
;     ...
;     const float mu = wsum(s) * (1.f / 1024.f);
;     float q = 0.f;
;     for (int i = 0; i < 4; ++i) { float a = v[i].x - mu, b = v[i].y - mu, c = v[i].z - mu, d = v[i].w - mu; q += a * a + b * b + c * c + d * d; }
;     const float rstd = rsqrtf(wsum(q) * (1.f / 1024.f) + LN_EPS);
;     float pg[8];
; #pragma unroll
;     for (int j = 0; j < 8; ++j) pg[j] = 0.f;
; #pragma unroll
;     for (int i = 0; i < 4; ++i) {
;       const int c0 = i * 256 + lane * 4;
;       float4 gg = *(const float4*)(g + c0), bb = *(const float4*)(bta + c0);
;       float y[4];
;       y[0] = (v[i].x - mu) * rstd * gg.x + bb.x; y[1] = (v[i].y - mu) * rstd * gg.y + bb.y; y[2] = (v[i].z - mu) * rstd * gg.z + bb.z; y[3] = (v[i].w - mu) * rstd * gg.w + bb.w;
;       uint2 o; o.x = pack2(y[0], y[1]); o.y = pack2(y[2], y[3]);
;       *(uint2*)(dst + (size_t)row * 1024 + c0) = o;
; #pragma unroll
;       for (int e = 0; e < 4; ++e) {
;         const float4 w0 = *(const float4*)(Wg + (c0 + e) * 8), w1 = *(const float4*)(Wg + (c0 + e) * 8 + 4);
;         pg[0] += y[e] * w0.x; pg[1] += y[e] * w0.y; pg[2] += y[e] * w0.z; pg[3] += y[e] * w0.w;
;         pg[4] += y[e] * w1.x; pg[5] += y[e] * w1.y; pg[6] += y[e] * w1.z; pg[7] += y[e] * w1.w;
	v_pk_add_f32 v[186:187], v[186:187], v[234:235] op_sel_hi:[1,0] neg_lo:[0,1] neg_hi:[0,1]
	v_mov_b32_e32 v240, v191
	v_mov_b32_e32 v241, v187
	v_pk_add_f32 v[192:193], v[192:193], v[234:235] op_sel_hi:[1,0] neg_lo:[0,1] neg_hi:[0,1]
	v_pk_add_f32 v[188:189], v[188:189], v[234:235] op_sel_hi:[1,0] neg_lo:[0,1] neg_hi:[0,1]
	v_pk_add_f32 v[182:183], v[182:183], v[234:235] op_sel_hi:[1,0] neg_lo:[0,1] neg_hi:[0,1]
	v_pk_add_f32 v[236:237], v[180:181], v[234:235] op_sel_hi:[1,0] neg_lo:[0,1] neg_hi:[0,1]
	v_pk_add_f32 v[180:181], v[178:179], v[234:235] op_sel_hi:[1,0] neg_lo:[0,1] neg_hi:[0,1]
	v_mov_b32_e32 v238, v190
	v_mov_b32_e32 v239, v186
	v_pk_mul_f32 v[240:241], v[240:241], v[240:241]
	v_mov_b32_e32 v178, v192
	v_mov_b32_e32 v179, v188
	v_pk_fma_f32 v[238:239], v[238:239], v[238:239], v[240:241]
	v_mov_b32_e32 v240, v181
	v_mov_b32_e32 v241, v183
	v_pk_add_f32 v[184:185], v[184:185], v[234:235] op_sel_hi:[1,0] neg_lo:[0,1] neg_hi:[0,1]
	v_pk_fma_f32 v[178:179], v[178:179], v[178:179], v[238:239]
	v_mov_b32_e32 v238, v180
	v_mov_b32_e32 v239, v182
	v_pk_mul_f32 v[240:241], v[240:241], v[240:241]
	v_mov_b32_e32 v234, v193
	v_mov_b32_e32 v235, v189
	v_mov_b32_e32 v242, v236
	v_mov_b32_e32 v243, v184
	v_pk_fma_f32 v[238:239], v[238:239], v[238:239], v[240:241]
	v_pk_fma_f32 v[178:179], v[234:235], v[234:235], v[178:179]
	v_mov_b32_e32 v234, v237
	v_mov_b32_e32 v235, v185
	v_pk_fma_f32 v[238:239], v[242:243], v[242:243], v[238:239]
	v_add_f32_e32 v178, v178, v179
	v_pk_fma_f32 v[234:235], v[234:235], v[234:235], v[238:239]
	v_ashrrev_i32_e32 v195, 31, v194
	v_add_f32_e32 v178, v235, v178
	v_add_f32_e32 v178, v234, v178
	s_nop 1
	v_add_f32_dpp v178, v178, v178 row_shr:1 row_mask:0xf bank_mask:0xf
	s_nop 1
	v_add_f32_dpp v178, v178, v178 row_shr:2 row_mask:0xf bank_mask:0xf
	s_nop 1
	v_add_f32_dpp v178, v178, v178 row_shr:4 row_mask:0xf bank_mask:0xf
	s_nop 1
	v_add_f32_dpp v178, v178, v178 row_shr:8 row_mask:0xf bank_mask:0xf
	s_nop 1
	v_add_f32_dpp v178, v178, v178 row_bcast:15 row_mask:0xa bank_mask:0xf
	s_nop 1
	v_add_f32_dpp v178, v178, v178 row_bcast:31 row_mask:0xc bank_mask:0xf
	s_nop 0
	v_readlane_b32 s73, v178, 63
	s_nop 1
	v_mov_b32_e32 v178, s73
	v_fmamk_f32 v178, v178, 0x3a800000, v215
	v_mul_f32_e32 v179, 0x4b800000, v178
	v_cmp_gt_f32_e64 s[8:9], s12, v178
	s_nop 1
	v_cndmask_b32_e64 v178, v178, v179, s[8:9]
	v_rsq_f32_e32 v217, v178
	v_lshlrev_b64 v[178:179], 11, v[194:195]
	v_lshl_add_u64 v[178:179], v[230:231], 0, v[178:179]
	v_mul_f32_e32 v219, 0x45800000, v217
	v_cndmask_b32_e64 v238, v217, v219, s[8:9]
	v_pk_mul_f32 v[190:191], v[190:191], v[238:239] op_sel_hi:[1,0]
	v_pk_mul_f32 v[234:235], v[192:193], v[238:239] op_sel_hi:[1,0]
	v_pk_mul_f32 v[182:183], v[182:183], v[238:239] op_sel_hi:[1,0]
	v_pk_fma_f32 v[192:193], v[2:3], v[190:191], v[6:7]
	v_pk_mul_f32 v[240:241], v[184:185], v[238:239] op_sel_hi:[1,0]
	v_pk_fma_f32 v[184:185], v[18:19], v[182:183], v[22:23]
	v_pk_mul_f32 v[182:183], v[236:237], v[238:239] op_sel_hi:[1,0]
	v_pk_fma_f32 v[236:237], v[34:35], v[192:193], 0 op_sel_hi:[1,0,0]
	v_pk_mul_f32 v[186:187], v[186:187], v[238:239] op_sel_hi:[1,0]
	v_pk_mul_f32 v[188:189], v[188:189], v[238:239] op_sel_hi:[1,0]
	v_pk_mul_f32 v[180:181], v[180:181], v[238:239] op_sel_hi:[1,0]
	v_pk_fma_f32 v[234:235], v[4:5], v[234:235], v[8:9]
	v_pk_fma_f32 v[236:237], v[42:43], v[192:193], v[236:237] op_sel:[0,1,0]
	v_pk_fma_f32 v[238:239], v[36:37], v[192:193], 0 op_sel_hi:[1,0,0]
	v_pk_fma_f32 v[236:237], v[50:51], v[234:235], v[236:237] op_sel_hi:[1,0,1]
	v_pk_fma_f32 v[238:239], v[44:45], v[192:193], v[238:239] op_sel:[0,1,0]
	v_pk_fma_f32 v[190:191], v[10:11], v[186:187], v[14:15]
	v_pk_fma_f32 v[186:187], v[20:21], v[240:241], v[24:25]
	v_pk_fma_f32 v[236:237], v[58:59], v[234:235], v[236:237] op_sel:[0,1,0]
	v_pk_fma_f32 v[238:239], v[52:53], v[234:235], v[238:239] op_sel_hi:[1,0,1]
	v_pk_fma_f32 v[240:241], v[38:39], v[192:193], 0 op_sel_hi:[1,0,0]
	v_pk_fma_f32 v[236:237], v[66:67], v[190:191], v[236:237] op_sel_hi:[1,0,1]
	v_pk_fma_f32 v[238:239], v[60:61], v[234:235], v[238:239] op_sel:[0,1,0]
	v_pk_fma_f32 v[240:241], v[46:47], v[192:193], v[240:241] op_sel:[0,1,0]
	v_pk_fma_f32 v[188:189], v[12:13], v[188:189], v[16:17]
	v_pk_fma_f32 v[236:237], v[74:75], v[190:191], v[236:237] op_sel:[0,1,0]
	v_pk_fma_f32 v[238:239], v[68:69], v[190:191], v[238:239] op_sel_hi:[1,0,1]
	v_pk_fma_f32 v[240:241], v[54:55], v[234:235], v[240:241] op_sel_hi:[1,0,1]
	v_pk_fma_f32 v[242:243], v[40:41], v[192:193], 0 op_sel_hi:[1,0,0]
	v_pk_fma_f32 v[236:237], v[82:83], v[188:189], v[236:237] op_sel_hi:[1,0,1]
	v_pk_fma_f32 v[238:239], v[76:77], v[190:191], v[238:239] op_sel:[0,1,0]
	v_pk_fma_f32 v[240:241], v[62:63], v[234:235], v[240:241] op_sel:[0,1,0]
	v_pk_fma_f32 v[242:243], v[48:49], v[192:193], v[242:243] op_sel:[0,1,0]
	v_pk_fma_f32 v[236:237], v[90:91], v[188:189], v[236:237] op_sel:[0,1,0]
	v_pk_fma_f32 v[238:239], v[84:85], v[188:189], v[238:239] op_sel_hi:[1,0,1]
	v_pk_fma_f32 v[240:241], v[70:71], v[190:191], v[240:241] op_sel_hi:[1,0,1]
	v_pk_fma_f32 v[242:243], v[56:57], v[234:235], v[242:243] op_sel_hi:[1,0,1]
	v_pk_fma_f32 v[236:237], v[98:99], v[184:185], v[236:237] op_sel_hi:[1,0,1]
	v_pk_fma_f32 v[238:239], v[92:93], v[188:189], v[238:239] op_sel:[0,1,0]
	v_pk_fma_f32 v[240:241], v[78:79], v[190:191], v[240:241] op_sel:[0,1,0]
	v_pk_fma_f32 v[242:243], v[64:65], v[234:235], v[242:243] op_sel:[0,1,0]
	v_pk_fma_f32 v[236:237], v[106:107], v[184:185], v[236:237] op_sel:[0,1,0]
	v_pk_fma_f32 v[238:239], v[100:101], v[184:185], v[238:239] op_sel_hi:[1,0,1]
	v_pk_fma_f32 v[240:241], v[86:87], v[188:189], v[240:241] op_sel_hi:[1,0,1]
; DI unsigned pack2(float a, float b) { const f32x2 v = {a, b}; return __builtin_bit_cast(unsigned, __builtin_convertvector(v, bf16v2)); }
; DI void ln_in_rows(const float* __restrict__ src, const float* __restrict__ g, const float* __restrict__ bta, const float* __restrict__ w_in, u16* __restrict__ dst, float* __restrict__ G, float* Wg) {
;     ...
;     for (int i = 0; i < 4; ++i) {
;       const int c0 = i * 256 + lane * 4;
;       float4 gg = *(const float4*)(g + c0), bb = *(const float4*)(bta + c0);
;       float y[4];
;       y[0] = (v[i].x - mu) * rstd * gg.x + bb.x; y[1] = (v[i].y - mu) * rstd * gg.y + bb.y; y[2] = (v[i].z - mu) * rstd * gg.z + bb.z; y[3] = (v[i].w - mu) * rstd * gg.w + bb.w;
;       uint2 o; o.x = pack2(y[0], y[1]); o.y = pack2(y[2], y[3]);
;       *(uint2*)(dst + (size_t)row * 1024 + c0) = o;
; #pragma unroll
;       for (int e = 0; e < 4; ++e) {
;         const float4 w0 = *(const float4*)(Wg + (c0 + e) * 8), w1 = *(const float4*)(Wg + (c0 + e) * 8 + 4);
;         pg[0] += y[e] * w0.x; pg[1] += y[e] * w0.y; pg[2] += y[e] * w0.z; pg[3] += y[e] * w0.w;
;         pg[4] += y[e] * w1.x; pg[5] += y[e] * w1.y; pg[6] += y[e] * w1.z; pg[7] += y[e] * w1.w;
;       }
;     }
; #pragma unroll
;     for (int off = 32; off >= 8; off >>= 1) {
;       const bool up = (lane & off) != 0;
;       const int nkeep = off >> 3;
; #pragma unroll
;       for (int i = 0; i < 4; ++i) if (i < nkeep) {
;         const float send = up ? pg[i] : pg[i + nkeep];
;         const float keep = up ? pg[i + nkeep] : pg[i];
;         pg[i] = keep + __shfl_xor(send, off);
;       }
;     }
;     float tot = pg[0];
;     tot += __shfl_xor(tot, 4); tot += __shfl_xor(tot, 2); tot += __shfl_xor(tot, 1);
	v_pk_fma_f32 v[242:243], v[72:73], v[190:191], v[242:243] op_sel_hi:[1,0,1]
	v_pk_fma_f32 v[236:237], v[114:115], v[186:187], v[236:237] op_sel_hi:[1,0,1]
	v_pk_fma_f32 v[238:239], v[108:109], v[184:185], v[238:239] op_sel:[0,1,0]
	v_pk_fma_f32 v[240:241], v[94:95], v[188:189], v[240:241] op_sel:[0,1,0]
	v_pk_fma_f32 v[242:243], v[80:81], v[190:191], v[242:243] op_sel:[0,1,0]
	v_pk_fma_f32 v[180:181], v[26:27], v[180:181], v[30:31]
	v_pk_fma_f32 v[236:237], v[122:123], v[186:187], v[236:237] op_sel:[0,1,0]
	v_pk_fma_f32 v[238:239], v[116:117], v[186:187], v[238:239] op_sel_hi:[1,0,1]
	v_pk_fma_f32 v[240:241], v[102:103], v[184:185], v[240:241] op_sel_hi:[1,0,1]
	v_pk_fma_f32 v[242:243], v[88:89], v[188:189], v[242:243] op_sel_hi:[1,0,1]
	v_pk_fma_f32 v[236:237], v[130:131], v[180:181], v[236:237] op_sel_hi:[1,0,1]
	v_pk_fma_f32 v[238:239], v[124:125], v[186:187], v[238:239] op_sel:[0,1,0]
	v_pk_fma_f32 v[240:241], v[110:111], v[184:185], v[240:241] op_sel:[0,1,0]
	v_pk_fma_f32 v[242:243], v[96:97], v[188:189], v[242:243] op_sel:[0,1,0]
	v_pk_fma_f32 v[182:183], v[28:29], v[182:183], v[32:33]
	v_pk_fma_f32 v[236:237], v[138:139], v[180:181], v[236:237] op_sel:[0,1,0]
	v_pk_fma_f32 v[238:239], v[132:133], v[180:181], v[238:239] op_sel_hi:[1,0,1]
	v_pk_fma_f32 v[240:241], v[118:119], v[186:187], v[240:241] op_sel_hi:[1,0,1]
	v_pk_fma_f32 v[242:243], v[104:105], v[184:185], v[242:243] op_sel_hi:[1,0,1]
	v_pk_fma_f32 v[236:237], v[146:147], v[182:183], v[236:237] op_sel_hi:[1,0,1]
	v_pk_fma_f32 v[238:239], v[140:141], v[180:181], v[238:239] op_sel:[0,1,0]
	v_pk_fma_f32 v[240:241], v[126:127], v[186:187], v[240:241] op_sel:[0,1,0]
	v_pk_fma_f32 v[242:243], v[112:113], v[184:185], v[242:243] op_sel:[0,1,0]
	v_pk_fma_f32 v[236:237], v[154:155], v[182:183], v[236:237] op_sel:[0,1,0]
	v_pk_fma_f32 v[238:239], v[148:149], v[182:183], v[238:239] op_sel_hi:[1,0,1]
	v_pk_fma_f32 v[240:241], v[180:181], v[134:135], v[240:241] op_sel_hi:[0,1,1]
	v_pk_fma_f32 v[242:243], v[120:121], v[186:187], v[242:243] op_sel_hi:[1,0,1]
	v_pk_fma_f32 v[238:239], v[156:157], v[182:183], v[238:239] op_sel:[0,1,0]
	v_pk_fma_f32 v[240:241], v[180:181], v[142:143], v[240:241] op_sel:[1,0,0]
	v_pk_fma_f32 v[242:243], v[128:129], v[186:187], v[242:243] op_sel:[0,1,0]
	v_pk_fma_f32 v[240:241], v[182:183], v[150:151], v[240:241] op_sel_hi:[0,1,1]
	v_pk_fma_f32 v[242:243], v[180:181], v[136:137], v[242:243] op_sel_hi:[0,1,1]
	v_pk_fma_f32 v[240:241], v[182:183], v[158:159], v[240:241] op_sel:[1,0,0]
	v_pk_fma_f32 v[242:243], v[180:181], v[144:145], v[242:243] op_sel:[1,0,0]
	v_pk_fma_f32 v[242:243], v[182:183], v[152:153], v[242:243] op_sel_hi:[0,1,1]
	v_pk_fma_f32 v[242:243], v[182:183], v[160:161], v[242:243] op_sel:[1,0,0]
	v_cvt_pk_bf16_f32 v192, v192, v193
	v_cvt_pk_bf16_f32 v193, v234, v235
	global_store_dwordx2 v[178:179], v[192:193], off
	v_cvt_pk_bf16_f32 v190, v190, v191
	v_cvt_pk_bf16_f32 v191, v188, v189
	v_cvt_pk_bf16_f32 v188, v184, v185
	v_cvt_pk_bf16_f32 v189, v186, v187
	v_cvt_pk_bf16_f32 v180, v180, v181
	v_cvt_pk_bf16_f32 v181, v182, v183
	global_store_dwordx2 v[178:179], v[190:191], off offset:512
	global_store_dwordx2 v[178:179], v[188:189], off offset:1024
	global_store_dwordx2 v[178:179], v[180:181], off offset:1536
	v_add_f32_dpp v236, v236, v236 row_shr:1 row_mask:0xf bank_mask:0xf
	v_add_f32_dpp v237, v237, v237 row_shr:1 row_mask:0xf bank_mask:0xf
	v_add_f32_dpp v238, v238, v238 row_shr:1 row_mask:0xf bank_mask:0xf
	v_add_f32_dpp v239, v239, v239 row_shr:1 row_mask:0xf bank_mask:0xf
	v_add_f32_dpp v240, v240, v240 row_shr:1 row_mask:0xf bank_mask:0xf
	v_add_f32_dpp v241, v241, v241 row_shr:1 row_mask:0xf bank_mask:0xf
	v_add_f32_dpp v242, v242, v242 row_shr:1 row_mask:0xf bank_mask:0xf
	v_add_f32_dpp v243, v243, v243 row_shr:1 row_mask:0xf bank_mask:0xf
	v_add_f32_dpp v236, v236, v236 row_shr:2 row_mask:0xf bank_mask:0xf
	v_add_f32_dpp v237, v237, v237 row_shr:2 row_mask:0xf bank_mask:0xf
	v_add_f32_dpp v238, v238, v238 row_shr:2 row_mask:0xf bank_mask:0xf
	v_add_f32_dpp v239, v239, v239 row_shr:2 row_mask:0xf bank_mask:0xf
	v_add_f32_dpp v240, v240, v240 row_shr:2 row_mask:0xf bank_mask:0xf
	v_add_f32_dpp v241, v241, v241 row_shr:2 row_mask:0xf bank_mask:0xf
	v_add_f32_dpp v242, v242, v242 row_shr:2 row_mask:0xf bank_mask:0xf
	v_add_f32_dpp v243, v243, v243 row_shr:2 row_mask:0xf bank_mask:0xf
; DI void ln_in_rows(const float* __restrict__ src, const float* __restrict__ g, const float* __restrict__ bta, const float* __restrict__ w_in, u16* __restrict__ dst, float* __restrict__ G, float* Wg) {
;     ...
; #pragma unroll
;     for (int off = 32; off >= 8; off >>= 1) {
;       const bool up = (lane & off) != 0;
;       const int nkeep = off >> 3;
; #pragma unroll
;       for (int i = 0; i < 4; ++i) if (i < nkeep) {
;         const float send = up ? pg[i] : pg[i + nkeep];
;         const float keep = up ? pg[i + nkeep] : pg[i];
;         pg[i] = keep + __shfl_xor(send, off);
;       }
;     }
;     float tot = pg[0];
;     tot += __shfl_xor(tot, 4); tot += __shfl_xor(tot, 2); tot += __shfl_xor(tot, 1);
;     if ((lane & 7) == 0) G[(size_t)row * 8 + (lane >> 3)] = tot;
;   }
; __global__ void __launch_bounds__(512) mega(Params p) {
;     ...
;   grid.sync();
	v_add_f32_dpp v236, v236, v236 row_shr:4 row_mask:0xf bank_mask:0xf
	v_add_f32_dpp v237, v237, v237 row_shr:4 row_mask:0xf bank_mask:0xf
	v_add_f32_dpp v238, v238, v238 row_shr:4 row_mask:0xf bank_mask:0xf
	v_add_f32_dpp v239, v239, v239 row_shr:4 row_mask:0xf bank_mask:0xf
	v_add_f32_dpp v240, v240, v240 row_shr:4 row_mask:0xf bank_mask:0xf
	v_add_f32_dpp v241, v241, v241 row_shr:4 row_mask:0xf bank_mask:0xf
	v_add_f32_dpp v242, v242, v242 row_shr:4 row_mask:0xf bank_mask:0xf
	v_add_f32_dpp v243, v243, v243 row_shr:4 row_mask:0xf bank_mask:0xf
	v_add_f32_dpp v236, v236, v236 row_shr:8 row_mask:0xf bank_mask:0xf
	v_add_f32_dpp v237, v237, v237 row_shr:8 row_mask:0xf bank_mask:0xf
	v_add_f32_dpp v238, v238, v238 row_shr:8 row_mask:0xf bank_mask:0xf
	v_add_f32_dpp v239, v239, v239 row_shr:8 row_mask:0xf bank_mask:0xf
	v_add_f32_dpp v240, v240, v240 row_shr:8 row_mask:0xf bank_mask:0xf
	v_add_f32_dpp v241, v241, v241 row_shr:8 row_mask:0xf bank_mask:0xf
	v_add_f32_dpp v242, v242, v242 row_shr:8 row_mask:0xf bank_mask:0xf
	v_add_f32_dpp v243, v243, v243 row_shr:8 row_mask:0xf bank_mask:0xf
	v_add_f32_dpp v236, v236, v236 row_bcast:15 row_mask:0xa bank_mask:0xf
	v_add_f32_dpp v237, v237, v237 row_bcast:15 row_mask:0xa bank_mask:0xf
	v_add_f32_dpp v238, v238, v238 row_bcast:15 row_mask:0xa bank_mask:0xf
	v_add_f32_dpp v239, v239, v239 row_bcast:15 row_mask:0xa bank_mask:0xf
	v_add_f32_dpp v240, v240, v240 row_bcast:15 row_mask:0xa bank_mask:0xf
	v_add_f32_dpp v241, v241, v241 row_bcast:15 row_mask:0xa bank_mask:0xf
	v_add_f32_dpp v242, v242, v242 row_bcast:15 row_mask:0xa bank_mask:0xf
	v_add_f32_dpp v243, v243, v243 row_bcast:15 row_mask:0xa bank_mask:0xf
	v_add_f32_dpp v236, v236, v236 row_bcast:31 row_mask:0xc bank_mask:0xf
	v_add_f32_dpp v237, v237, v237 row_bcast:31 row_mask:0xc bank_mask:0xf
	v_add_f32_dpp v238, v238, v238 row_bcast:31 row_mask:0xc bank_mask:0xf
	v_add_f32_dpp v239, v239, v239 row_bcast:31 row_mask:0xc bank_mask:0xf
	v_add_f32_dpp v240, v240, v240 row_bcast:31 row_mask:0xc bank_mask:0xf
	v_add_f32_dpp v241, v241, v241 row_bcast:31 row_mask:0xc bank_mask:0xf
	v_add_f32_dpp v242, v242, v242 row_bcast:31 row_mask:0xc bank_mask:0xf
	v_add_f32_dpp v243, v243, v243 row_bcast:31 row_mask:0xc bank_mask:0xf
	v_readlane_b32 s72, v236, 63
	v_readlane_b32 s73, v237, 63
	v_readlane_b32 s74, v238, 63
	v_readlane_b32 s75, v239, 63
	v_readlane_b32 s76, v240, 63
	v_readlane_b32 s77, v241, 63
	v_readlane_b32 s78, v242, 63
	v_readlane_b32 s79, v243, 63
	v_writelane_b32 v217, s72, 0
	v_writelane_b32 v217, s73, 8
	v_writelane_b32 v217, s74, 16
	v_writelane_b32 v217, s75, 24
	v_writelane_b32 v217, s76, 32
	v_writelane_b32 v217, s77, 40
	v_writelane_b32 v217, s78, 48
	v_writelane_b32 v217, s79, 56
	s_and_saveexec_b64 s[8:9], vcc
	s_cbranch_execz .Lln_botO
	v_lshlrev_b64 v[178:179], 5, v[194:195]
	v_lshl_add_u64 v[178:179], v[200:201], 0, v[178:179]
	global_store_dword v[178:179], v217, off
.Lln_botO:
	s_or_b64 exec, exec, s[8:9]
	s_waitcnt vmcnt(14)
	s_and_b64 s[0:1], exec, s[0:1]
	s_or_b64 s[6:7], s[0:1], s[6:7]
	v_mov_b32_e32 v194, v232
	v_mov_b64_e32 v[190:191], v[204:205]
	v_mov_b64_e32 v[192:193], v[206:207]
	v_mov_b64_e32 v[186:187], v[208:209]
	v_mov_b64_e32 v[188:189], v[210:211]
	v_mov_b64_e32 v[182:183], v[224:225]
	v_mov_b64_e32 v[184:185], v[226:227]
	v_mov_b64_e32 v[178:179], v[244:245]
	v_mov_b64_e32 v[180:181], v[246:247]
	s_waitcnt lgkmcnt(0)
	s_andn2_b64 exec, exec, s[6:7]
	s_cbranch_execz .LBB0_172
	s_branch .LBB0_168
.LBB0_172:
	s_waitcnt vmcnt(0)
	s_or_b64 exec, exec, s[4:5]
	v_lshrrev_b32_e32 v1, 20, v0
	v_lshrrev_b32_e32 v0, 10, v0
	v_or_b32_e32 v0, v0, v1
	s_movk_i32 s0, 0x3ff
	v_and_or_b32 v0, v0, s0, v222
	v_cmp_eq_u32_e32 vcc, 0, v0
	s_barrier
	s_and_saveexec_b64 s[0:1], vcc
	s_xor_b64 s[0:1], exec, s[0:1]
	v_writelane_b32 v250, s18, 48
	s_nop 1
	v_writelane_b32 v250, s19, 49
	s_cbranch_execz .LBB0_182
	v_readlane_b32 s2, v250, 0
	v_readlane_b32 s3, v250, 1
	buffer_wbl2 sc1
	s_waitcnt vmcnt(0)
	s_load_dwordx2 s[4:5], s[2:3], 0x58
	v_mov_b32_e32 v2, 0
	s_mov_b64 s[6:7], exec
	v_mbcnt_lo_u32_b32 v1, s6, 0
	v_mbcnt_hi_u32_b32 v1, s7, v1
	s_waitcnt lgkmcnt(0)
	global_load_dword v0, v2, s[4:5] offset:40
	v_cmp_eq_u32_e32 vcc, 0, v1
	s_and_saveexec_b64 s[8:9], vcc
	s_cbranch_execz .LBB0_175
	s_bcnt1_i32_b64 s2, s[6:7]
	v_mov_b32_e32 v3, s2
	global_atomic_add v3, v2, v3, s[4:5] offset:32 sc0
